# scan phase rewritten by hand: LDS-DMA staging into swizzled images, all fragment reads hoisted with counted waits, 1-chunk prefetch; same bf16 MFMA math
# speedup vs baseline: 1.0130x; 1.0130x over previous
.LBB0_362:
	v_readlane_b32 s4, v242, 8
	s_waitcnt lgkmcnt(0)
	s_barrier
	v_mbcnt_lo_u32_b32 v0, -1, 0
	v_mbcnt_hi_u32_b32 v0, -1, v0
	s_mov_b32 s4, s40
	s_mov_b32 s5, s77
	v_and_b32_e32 v1, 15, v0
	v_lshrrev_b32_e32 v2, 4, v0
	s_lshr_b32 s38, s5, 1
	s_and_b32 s39, s5, 1
	s_lshr_b32 s7, s4, 2
	s_lshl_b32 s7, s7, 5
	s_and_b32 s8, s4, 3
	s_lshl_b32 s9, s7, 14
	s_add_u32 s10, s92, 0x9000000
	s_addc_u32 s11, s93, 0
	s_add_u32 s10, s10, s9
	s_addc_u32 s11, s11, 0
	s_add_u32 s12, s92, 0xb000000
	s_addc_u32 s13, s93, 0
	s_add_u32 s12, s12, s9
	s_addc_u32 s13, s13, 0
	s_add_u32 s14, s92, 0xd000000
	s_addc_u32 s15, s93, 0
	s_add_u32 s14, s14, s9
	s_addc_u32 s15, s15, 0
	s_lshl_b32 s26, s7, 13
	s_add_u32 s18, s92, 0xf000000
	s_addc_u32 s19, s93, 0
	s_add_u32 s18, s18, s26
	s_addc_u32 s19, s19, 0
	s_add_u32 s24, s90, 0x2000000
	s_addc_u32 s25, s91, 0
	s_add_u32 s24, s24, s9
	s_addc_u32 s25, s25, 0
	s_lshl_b32 s26, s8, 6
	s_add_u32 s24, s24, s26
	s_addc_u32 s25, s25, 0
	s_add_u32 s42, s92, 0x500000
	s_addc_u32 s43, s93, 0
	v_and_b32_e32 v26, 31, v0
	v_add_u32_e32 v26, s7, v26
	v_lshlrev_b32_e32 v26, 2, v26
	global_load_dword v24, v26, s[42:43]
	v_mov_b32_e32 v30, 0
	s_lshl_b32 s30, s5, 11
	s_lshl_b32 s31, s5, 10
	s_and_b32 s32, s5, 3
	s_lshl_b32 s32, s32, 10
	s_lshl_b32 s7, s5, 3
	v_add_u32_e32 v26, s7, v2
	v_and_b32_e32 v27, 15, v26
	v_xor_b32_e32 v27, v27, v1
	v_lshlrev_b32_e32 v27, 4, v27
	v_lshl_add_u32 v3, v26, 8, v27
	s_lshl_b32 s7, s5, 3
	s_add_u32 s7, s7, 4
	v_add_u32_e32 v26, s7, v2
	v_and_b32_e32 v27, 15, v26
	v_xor_b32_e32 v27, v27, v1
	v_lshlrev_b32_e32 v27, 4, v27
	v_lshl_add_u32 v4, v26, 8, v27
	v_lshrrev_b32_e32 v28, 3, v0
	v_and_b32_e32 v29, 7, v0
	s_lshl_b32 s7, s5, 4
	v_add_u32_e32 v26, s7, v28
	v_bfe_u32 v27, v26, 1, 3
	v_xor_b32_e32 v27, v27, v29
	v_lshlrev_b32_e32 v27, 4, v27
	v_lshl_add_u32 v5, v26, 7, v27
	s_lshl_b32 s7, s5, 4
	s_add_u32 s7, s7, 8
	v_add_u32_e32 v26, s7, v28
	v_bfe_u32 v27, v26, 1, 3
	v_xor_b32_e32 v27, v27, v29
	v_lshlrev_b32_e32 v27, 4, v27
	v_lshl_add_u32 v6, v26, 7, v27
	s_lshl_b32 s7, s5, 3
	v_add_u32_e32 v26, s7, v28
	v_bfe_u32 v27, v26, 1, 3
	v_xor_b32_e32 v27, v27, v29
	v_lshlrev_b32_e32 v27, 4, v27
	v_lshl_add_u32 v7, v26, 7, v27
	s_and_b32 s7, s5, 3
	s_lshl_b32 s7, s7, 4
	v_lshrrev_b32_e32 v26, 2, v0
	v_add_u32_e32 v26, s7, v26
	v_and_b32_e32 v27, 3, v0
	v_lshlrev_b32_e32 v27, 4, v27
	v_lshl_add_u32 v8, v26, 8, v27
	s_lshl_b32 s7, s39, 4
	v_add_u32_e32 v26, s7, v1
	s_lshl_b32 s8, s38, 4
	v_add_u32_e32 v27, s8, v1
	v_lshlrev_b32_e32 v28, 4, v2
	s_movk_i32 s9, 0x110
	v_mul_lo_u32 v29, v26, s9
	v_add_u32_e32 v10, v29, v28
	v_add_u32_e32 v10, 0x1c000, v10
	v_lshlrev_b32_e32 v31, 3, v2
	s_lshl_b32 s9, s38, 6
	v_add3_u32 v21, v29, v31, s9
	v_add_u32_e32 v21, 0x1c000, v21
	s_movk_i32 s9, 0x90
	v_mul_lo_u32 v29, v26, s9
	v_add_u32_e32 v19, v29, v28
	v_add_u32_e32 v19, 0x1e200, v19
	s_lshl_b32 s9, s38, 5
	v_add3_u32 v20, v29, v31, s9
	v_add_u32_e32 v20, 0x1e200, v20
	v_add_u32_e32 v29, 0, v2
	v_xor_b32_e32 v29, v29, v1
	v_lshlrev_b32_e32 v29, 4, v29
	v_lshl_add_u32 v11, v27, 8, v29
	v_add_u32_e32 v29, 4, v2
	v_xor_b32_e32 v29, v29, v1
	v_lshlrev_b32_e32 v29, 4, v29
	v_lshl_add_u32 v12, v27, 8, v29
	v_add_u32_e32 v29, 8, v2
	v_xor_b32_e32 v29, v29, v1
	v_lshlrev_b32_e32 v29, 4, v29
	v_lshl_add_u32 v13, v27, 8, v29
	v_add_u32_e32 v29, 12, v2
	v_xor_b32_e32 v29, v29, v1
	v_lshlrev_b32_e32 v29, 4, v29
	v_lshl_add_u32 v14, v27, 8, v29
	v_lshrrev_b32_e32 v31, 1, v1
	s_lshl_b32 s9, s38, 5
	v_add_u32_e32 v26, s9, v1
	v_add_u32_e32 v29, 0, v2
	v_xor_b32_e32 v29, v29, v31
	v_lshlrev_b32_e32 v29, 4, v29
	v_lshl_add_u32 v15, v26, 7, v29
	v_add_u32_e32 v15, 0x10000, v15
	v_lshl_add_u32 v17, v27, 7, v29
	v_add_u32_e32 v17, 0x18000, v17
	v_add_u32_e32 v29, 4, v2
	v_xor_b32_e32 v29, v29, v31
	v_lshlrev_b32_e32 v29, 4, v29
	v_lshl_add_u32 v16, v26, 7, v29
	v_add_u32_e32 v16, 0x10000, v16
	v_lshl_add_u32 v18, v27, 7, v29
	v_add_u32_e32 v18, 0x18000, v18
	s_lshl_b32 s9, s38, 10
	v_lshlrev_b32_e32 v29, 8, v2
	v_add_u32_e32 v29, s9, v29
	s_lshl_b32 s9, s39, 5
	v_lshl_add_u32 v29, v1, 1, v29
	v_add_u32_e32 v29, s9, v29
	v_add_u32_e32 v22, 0x1f400, v29
	v_lshlrev_b32_e32 v29, 3, v2
	v_lshl_add_u32 v29, v27, 8, v29
	v_add_u32_e32 v9, s9, v29
	v_mov_b32_e32 v32, 0
	v_mov_b32_e32 v33, 0
	v_mov_b32_e32 v34, 0
	v_mov_b32_e32 v35, 0
	v_lshl_add_u32 v26, s5, 6, v0
	v_lshlrev_b32_e32 v27, 4, v26
	v_add_u32_e32 v27, 0x1c000, v27
	ds_write_b128 v27, v[32:35]
	v_and_b32_e32 v26, 31, v26
	v_lshlrev_b32_e32 v27, 4, v26
	v_add_u32_e32 v27, 0x1e000, v27
	ds_write_b128 v27, v[32:35]
	v_mov_b32_e32 v92, 0
	v_mov_b32_e32 v93, 0
	v_mov_b32_e32 v94, 0
	v_mov_b32_e32 v95, 0
	v_mov_b32_e32 v96, 0
	v_mov_b32_e32 v97, 0
	v_mov_b32_e32 v98, 0
	v_mov_b32_e32 v99, 0
	s_mov_b32 s6, 0
	global_load_dword v25, v30, s[42:43]
	global_load_dword v25, v30, s[42:43]
	global_load_dword v25, v30, s[42:43]
	s_add_i32 m0, s32, 0x1f400
	s_nop 0
	global_load_lds_dwordx4 v8, s[24:25]
	s_add_i32 m0, s30, 0x0
	s_nop 0
	global_load_lds_dwordx4 v3, s[10:11]
	s_add_i32 m0, s30, 0x400
	s_nop 0
	global_load_lds_dwordx4 v4, s[10:11]
	s_add_i32 m0, s30, 0x8000
	s_nop 0
	global_load_lds_dwordx4 v3, s[12:13]
	s_add_i32 m0, s30, 0x8400
	s_nop 0
	global_load_lds_dwordx4 v4, s[12:13]
	global_load_dword v25, v30, s[42:43]
	s_add_i32 m0, s30, 0x10000
	s_nop 0
	global_load_lds_dwordx4 v5, s[14:15]
	s_add_i32 m0, s30, 0x10400
	s_nop 0
	global_load_lds_dwordx4 v6, s[14:15]
	s_add_i32 m0, s31, 0x18000
	s_nop 0
	global_load_lds_dwordx4 v7, s[18:19]
	s_add_u32 s26, s24, 0x4000
	s_addc_u32 s27, s25, 0
	s_add_i32 m0, s32, 0x20400
	s_nop 0
	global_load_lds_dwordx4 v8, s[26:27]
	s_add_u32 s26, s10, 0x4000
	s_addc_u32 s27, s11, 0
	s_add_i32 m0, s30, 0x4000
	s_nop 0
	global_load_lds_dwordx4 v3, s[26:27]
	s_add_i32 m0, s30, 0x4400
	s_nop 0
	global_load_lds_dwordx4 v4, s[26:27]
	s_add_u32 s26, s12, 0x4000
	s_addc_u32 s27, s13, 0
	s_add_i32 m0, s30, 0xc000
	s_nop 0
	global_load_lds_dwordx4 v3, s[26:27]
	s_add_i32 m0, s30, 0xc400
	s_nop 0
	global_load_lds_dwordx4 v4, s[26:27]
	global_load_dword v25, v30, s[42:43]
	s_waitcnt vmcnt(10) lgkmcnt(0)
	s_barrier
.Lscan_loop:
	s_and_b32 s7, s6, 3
	s_lshl_b32 s7, s7, 12
	v_add_u32_e32 v23, s7, v22
	ds_read_b128 v[32:35], v10 offset:0
	ds_read_b128 v[48:51], v11 offset:0
	ds_read_b128 v[36:39], v10 offset:64
	ds_read_b128 v[52:55], v12 offset:0
	ds_read_b128 v[40:43], v10 offset:128
	ds_read_b128 v[56:59], v13 offset:0
	ds_read_b128 v[44:47], v10 offset:192
	ds_read_b128 v[60:63], v14 offset:0
	ds_read_u16 v80, v23 offset:0
	ds_read_u16 v81, v23 offset:64
	ds_read_u16 v82, v23 offset:128
	ds_read_u16 v83, v23 offset:192
	s_add_u32 s33, s6, 1
	s_min_u32 s33, s33, 31
	s_add_u32 s36, s6, 2
	s_min_u32 s36, s36, 31
	s_lshl_b32 s7, s33, 14
	s_add_u32 s26, s14, s7
	s_addc_u32 s27, s15, 0
	s_add_i32 m0, s30, 0x14000
	s_nop 0
	global_load_lds_dwordx4 v5, s[26:27]
	s_add_i32 m0, s30, 0x14400
	s_nop 0
	global_load_lds_dwordx4 v6, s[26:27]
	s_lshl_b32 s7, s33, 13
	s_add_u32 s28, s18, s7
	s_addc_u32 s29, s19, 0
	s_add_i32 m0, s31, 0x1a000
	s_nop 0
	global_load_lds_dwordx4 v7, s[28:29]
	s_lshl_b32 s7, s36, 14
	s_add_u32 s26, s24, s7
	s_addc_u32 s27, s25, 0
	s_add_u32 s8, s6, 2
	s_and_b32 s8, s8, 3
	s_lshl_b32 s8, s8, 12
	s_add_u32 s8, s8, s32
	s_add_i32 m0, s8, 0x1f400
	s_nop 0
	global_load_lds_dwordx4 v8, s[26:27]
	v_readlane_b32 s37, v24, s6
	s_nop 1
	v_mul_f32_e32 v92, s37, v92
	v_mul_f32_e32 v93, s37, v93
	v_mul_f32_e32 v94, s37, v94
	v_mul_f32_e32 v95, s37, v95
	v_mul_f32_e32 v96, s37, v96
	v_mul_f32_e32 v97, s37, v97
	v_mul_f32_e32 v98, s37, v98
	v_mul_f32_e32 v99, s37, v99
	s_waitcnt lgkmcnt(10)
	v_mfma_f32_16x16x32_bf16 v[84:87], v[48:51], v[32:35], 0
	s_waitcnt lgkmcnt(8)
	v_mfma_f32_16x16x32_bf16 v[84:87], v[52:55], v[36:39], v[84:87]
	s_waitcnt lgkmcnt(6)
	v_mfma_f32_16x16x32_bf16 v[84:87], v[56:59], v[40:43], v[84:87]
	s_waitcnt lgkmcnt(4)
	v_mfma_f32_16x16x32_bf16 v[84:87], v[60:63], v[44:47], v[84:87]
	ds_read_b128 v[64:67], v11 offset:32768
	ds_read_b128 v[68:71], v12 offset:32768
	ds_read_b128 v[72:75], v13 offset:32768
	ds_read_b128 v[76:79], v14 offset:32768
	s_waitcnt lgkmcnt(4)
	v_lshlrev_b32_e32 v80, 16, v80
	v_lshlrev_b32_e32 v81, 16, v81
	v_lshlrev_b32_e32 v82, 16, v82
	v_lshlrev_b32_e32 v83, 16, v83
	v_sub_f32_e32 v26, v80, v84
	v_sub_f32_e32 v27, v81, v85
	v_sub_f32_e32 v28, v82, v86
	v_sub_f32_e32 v29, v83, v87
	v_cvt_pk_bf16_f32 v26, v26, v27
	v_cvt_pk_bf16_f32 v27, v28, v29
	ds_write_b64 v20, v[26:27]
	s_waitcnt vmcnt(10) lgkmcnt(0)
	s_barrier
	ds_read_b128 v[100:103], v19
	ds_read_b128 v[108:111], v15 offset:0
	ds_read_b128 v[112:115], v15 offset:2048
	ds_read_b128 v[104:107], v19 offset:64
	ds_read_b128 v[116:119], v16 offset:0
	ds_read_b128 v[120:123], v16 offset:2048
	ds_read_b128 v[124:127], v17 offset:0
	ds_read_b128 v[128:131], v18 offset:0
	s_lshl_b32 s7, s36, 14
	s_add_u32 s26, s10, s7
	s_addc_u32 s27, s11, 0
	s_add_i32 m0, s30, 0x0
	s_nop 0
	global_load_lds_dwordx4 v3, s[26:27]
	s_add_i32 m0, s30, 0x400
	s_nop 0
	global_load_lds_dwordx4 v4, s[26:27]
	s_lshl_b32 s7, s36, 14
	s_add_u32 s28, s12, s7
	s_addc_u32 s29, s13, 0
	s_add_i32 m0, s30, 0x8000
	s_nop 0
	global_load_lds_dwordx4 v3, s[28:29]
	s_add_i32 m0, s30, 0x8400
	s_nop 0
	global_load_lds_dwordx4 v4, s[28:29]
	v_mfma_f32_16x16x32_bf16 v[88:91], v[32:35], v[64:67], 0
	v_mfma_f32_16x16x32_bf16 v[88:91], v[36:39], v[68:71], v[88:91]
	v_mfma_f32_16x16x32_bf16 v[88:91], v[40:43], v[72:75], v[88:91]
	v_mfma_f32_16x16x32_bf16 v[88:91], v[44:47], v[76:79], v[88:91]
	s_waitcnt lgkmcnt(6)
	v_mfma_f32_16x16x32_bf16 v[92:95], v[108:111], v[100:103], v[92:95]
	s_waitcnt lgkmcnt(5)
	v_mfma_f32_16x16x32_bf16 v[96:99], v[112:115], v[100:103], v[96:99]
	s_waitcnt lgkmcnt(3)
	v_mfma_f32_16x16x32_bf16 v[92:95], v[116:119], v[104:107], v[92:95]
	s_waitcnt lgkmcnt(2)
	v_mfma_f32_16x16x32_bf16 v[96:99], v[120:123], v[104:107], v[96:99]
	s_waitcnt lgkmcnt(1)
	v_mfma_f32_16x16x32_bf16 v[88:91], v[100:103], v[124:127], v[88:91]
	s_waitcnt lgkmcnt(0)
	v_mfma_f32_16x16x32_bf16 v[88:91], v[104:107], v[128:131], v[88:91]
	s_lshl_b32 s7, s6, 14
	s_add_u32 s28, s24, s7
	s_addc_u32 s29, s25, 0
	s_nop 1
	v_cvt_pk_bf16_f32 v26, v92, v93
	v_cvt_pk_bf16_f32 v27, v94, v95
	v_cvt_pk_bf16_f32 v28, v96, v97
	v_cvt_pk_bf16_f32 v29, v98, v99
	ds_write_b64 v21, v[26:27]
	ds_write_b64 v21, v[28:29] offset:32
	v_cvt_pk_bf16_f32 v80, v88, v89
	v_cvt_pk_bf16_f32 v81, v90, v91
	global_store_dwordx2 v9, v[80:81], s[28:29]
	s_add_u32 s6, s6, 1
	s_waitcnt vmcnt(10) lgkmcnt(0)
	s_barrier
	s_and_b32 s7, s6, 3
	s_lshl_b32 s7, s7, 12
	v_add_u32_e32 v23, s7, v22
	ds_read_b128 v[32:35], v10 offset:0
	ds_read_b128 v[48:51], v11 offset:16384
	ds_read_b128 v[36:39], v10 offset:64
	ds_read_b128 v[52:55], v12 offset:16384
	ds_read_b128 v[40:43], v10 offset:128
	ds_read_b128 v[56:59], v13 offset:16384
	ds_read_b128 v[44:47], v10 offset:192
	ds_read_b128 v[60:63], v14 offset:16384
	ds_read_u16 v80, v23 offset:0
	ds_read_u16 v81, v23 offset:64
	ds_read_u16 v82, v23 offset:128
	ds_read_u16 v83, v23 offset:192
	s_add_u32 s33, s6, 1
	s_min_u32 s33, s33, 31
	s_add_u32 s36, s6, 2
	s_min_u32 s36, s36, 31
	s_lshl_b32 s7, s33, 14
	s_add_u32 s26, s14, s7
	s_addc_u32 s27, s15, 0
	s_add_i32 m0, s30, 0x10000
	s_nop 0
	global_load_lds_dwordx4 v5, s[26:27]
	s_add_i32 m0, s30, 0x10400
	s_nop 0
	global_load_lds_dwordx4 v6, s[26:27]
	s_lshl_b32 s7, s33, 13
	s_add_u32 s28, s18, s7
	s_addc_u32 s29, s19, 0
	s_add_i32 m0, s31, 0x18000
	s_nop 0
	global_load_lds_dwordx4 v7, s[28:29]
	s_lshl_b32 s7, s36, 14
	s_add_u32 s26, s24, s7
	s_addc_u32 s27, s25, 0
	s_add_u32 s8, s6, 2
	s_and_b32 s8, s8, 3
	s_lshl_b32 s8, s8, 12
	s_add_u32 s8, s8, s32
	s_add_i32 m0, s8, 0x1f400
	s_nop 0
	global_load_lds_dwordx4 v8, s[26:27]
	v_readlane_b32 s37, v24, s6
	s_nop 1
	v_mul_f32_e32 v92, s37, v92
	v_mul_f32_e32 v93, s37, v93
	v_mul_f32_e32 v94, s37, v94
	v_mul_f32_e32 v95, s37, v95
	v_mul_f32_e32 v96, s37, v96
	v_mul_f32_e32 v97, s37, v97
	v_mul_f32_e32 v98, s37, v98
	v_mul_f32_e32 v99, s37, v99
	s_waitcnt lgkmcnt(10)
	v_mfma_f32_16x16x32_bf16 v[84:87], v[48:51], v[32:35], 0
	s_waitcnt lgkmcnt(8)
	v_mfma_f32_16x16x32_bf16 v[84:87], v[52:55], v[36:39], v[84:87]
	s_waitcnt lgkmcnt(6)
	v_mfma_f32_16x16x32_bf16 v[84:87], v[56:59], v[40:43], v[84:87]
	s_waitcnt lgkmcnt(4)
	v_mfma_f32_16x16x32_bf16 v[84:87], v[60:63], v[44:47], v[84:87]
	ds_read_b128 v[64:67], v11 offset:49152
	ds_read_b128 v[68:71], v12 offset:49152
	ds_read_b128 v[72:75], v13 offset:49152
	ds_read_b128 v[76:79], v14 offset:49152
	s_waitcnt lgkmcnt(4)
	v_lshlrev_b32_e32 v80, 16, v80
	v_lshlrev_b32_e32 v81, 16, v81
	v_lshlrev_b32_e32 v82, 16, v82
	v_lshlrev_b32_e32 v83, 16, v83
	v_sub_f32_e32 v26, v80, v84
	v_sub_f32_e32 v27, v81, v85
	v_sub_f32_e32 v28, v82, v86
	v_sub_f32_e32 v29, v83, v87
	v_cvt_pk_bf16_f32 v26, v26, v27
	v_cvt_pk_bf16_f32 v27, v28, v29
	ds_write_b64 v20, v[26:27]
	s_waitcnt vmcnt(10) lgkmcnt(0)
	s_barrier
	ds_read_b128 v[100:103], v19
	ds_read_b128 v[108:111], v15 offset:16384
	ds_read_b128 v[112:115], v15 offset:18432
	ds_read_b128 v[104:107], v19 offset:64
	ds_read_b128 v[116:119], v16 offset:16384
	ds_read_b128 v[120:123], v16 offset:18432
	ds_read_b128 v[124:127], v17 offset:8192
	ds_read_b128 v[128:131], v18 offset:8192
	s_lshl_b32 s7, s36, 14
	s_add_u32 s26, s10, s7
	s_addc_u32 s27, s11, 0
	s_add_i32 m0, s30, 0x4000
	s_nop 0
	global_load_lds_dwordx4 v3, s[26:27]
	s_add_i32 m0, s30, 0x4400
	s_nop 0
	global_load_lds_dwordx4 v4, s[26:27]
	s_lshl_b32 s7, s36, 14
	s_add_u32 s28, s12, s7
	s_addc_u32 s29, s13, 0
	s_add_i32 m0, s30, 0xc000
	s_nop 0
	global_load_lds_dwordx4 v3, s[28:29]
	s_add_i32 m0, s30, 0xc400
	s_nop 0
	global_load_lds_dwordx4 v4, s[28:29]
	v_mfma_f32_16x16x32_bf16 v[88:91], v[32:35], v[64:67], 0
	v_mfma_f32_16x16x32_bf16 v[88:91], v[36:39], v[68:71], v[88:91]
	v_mfma_f32_16x16x32_bf16 v[88:91], v[40:43], v[72:75], v[88:91]
	v_mfma_f32_16x16x32_bf16 v[88:91], v[44:47], v[76:79], v[88:91]
	s_waitcnt lgkmcnt(6)
	v_mfma_f32_16x16x32_bf16 v[92:95], v[108:111], v[100:103], v[92:95]
	s_waitcnt lgkmcnt(5)
	v_mfma_f32_16x16x32_bf16 v[96:99], v[112:115], v[100:103], v[96:99]
	s_waitcnt lgkmcnt(3)
	v_mfma_f32_16x16x32_bf16 v[92:95], v[116:119], v[104:107], v[92:95]
	s_waitcnt lgkmcnt(2)
	v_mfma_f32_16x16x32_bf16 v[96:99], v[120:123], v[104:107], v[96:99]
	s_waitcnt lgkmcnt(1)
	v_mfma_f32_16x16x32_bf16 v[88:91], v[100:103], v[124:127], v[88:91]
	s_waitcnt lgkmcnt(0)
	v_mfma_f32_16x16x32_bf16 v[88:91], v[104:107], v[128:131], v[88:91]
	s_lshl_b32 s7, s6, 14
	s_add_u32 s28, s24, s7
	s_addc_u32 s29, s25, 0
	s_nop 1
	v_cvt_pk_bf16_f32 v26, v92, v93
	v_cvt_pk_bf16_f32 v27, v94, v95
	v_cvt_pk_bf16_f32 v28, v96, v97
	v_cvt_pk_bf16_f32 v29, v98, v99
	ds_write_b64 v21, v[26:27]
	ds_write_b64 v21, v[28:29] offset:32
	v_cvt_pk_bf16_f32 v80, v88, v89
	v_cvt_pk_bf16_f32 v81, v90, v91
	global_store_dwordx2 v9, v[80:81], s[28:29]
	s_add_u32 s6, s6, 1
	s_waitcnt vmcnt(10) lgkmcnt(0)
	s_barrier
	s_cmp_lt_u32 s6, 32
	s_cbranch_scc1 .Lscan_loop
	s_lshl_b32 s56, s77, 5
	s_and_b32 s57, s40, 3
	s_lshl_b32 s72, s40, 5
	s_waitcnt vmcnt(0)
	v_readfirstlane_b32 s3, v194
	s_cmp_gt_u32 s3, 63
	s_barrier
	s_cbranch_scc1 .LBB0_421
	s_waitcnt vmcnt(2)
	v_mbcnt_lo_u32_b32 v0, -1, 0
	v_mbcnt_hi_u32_b32 v0, -1, v0
	s_nop 0
	v_cmp_eq_u32_e32 vcc, 0, v0
	s_and_saveexec_b64 s[6:7], vcc
	s_cbranch_execz .LBB0_420
	s_add_i32 s3, 0, 0x23ff0
	v_mov_b32_e32 v0, s3
	s_waitcnt vmcnt(0) expcnt(0) lgkmcnt(0)
	ds_read_b32 v2, v0
	s_add_i32 s3, 0, 0x23ff4
	v_mov_b32_e32 v0, s3
	ds_read_b32 v0, v0
	s_waitcnt lgkmcnt(1)
	v_cmp_ne_u32_e32 vcc, 0, v2
	s_cbranch_vccnz .LBB0_384
	s_mov_b32 s3, 1
	v_mov_b32_e32 v16, 0
	s_branch .LBB0_372
